# removed entry cg grid.sync (XCD barrier self-registers); c-vector GEMM K-loops skip MFMAs and LDS reads of the unused ai=1 row half (padding rows never stored)
# baseline (speedup 1.0000x reference)
; #define LAS __attribute__((address_space(3)))
; DI float silu(float x) { return x * __builtin_amdgcn_rcpf(1.f + ex2(-x * LOG2E)); }
; DI unsigned xb_add(unsigned* p, unsigned v) { return __hip_atomic_fetch_add(p, v, __ATOMIC_RELAXED, __HIP_MEMORY_SCOPE_AGENT); }
; DI unsigned xb_xcc_id() { return (unsigned)__builtin_amdgcn_s_getreg((3 << 11) | 20) & 0xFu; }
; #define PIN(i) gptr(P.in[i])
; #define PH_BEGIN const int tid = otid(); const int G = gridDim.x; const int bid = osi((int)blockIdx.x); unsigned char* ws = osp(P.ws); float* out = osp(P.out); unsigned char* U = ws + WS_U; (void)tid; (void)G; (void)bid; (void)out; (void)U;
; __global__ void __launch_bounds__(512, 2) mega(Params P) {
;     extern __shared__ __attribute__((aligned(16))) unsigned char lds_raw[];
;     LAS unsigned char* lds = (LAS unsigned char*)lds_raw;
;     cg::grid_group grid = cg::this_grid();
;     const int g_wave = __builtin_amdgcn_readfirstlane((int)threadIdx.x >> 6);
;     if (threadIdx.x == 0) { *(volatile LAS unsigned*)(lds + LDS_MISC + 8) = 0u; *(volatile LAS unsigned*)(lds + LDS_MISC + 12) = 0u; (void)xb_add((unsigned*)(gptr(P.ws) + WS_CTL) + XB_XCNT(xb_xcc_id()), 1u); }
;     __syncthreads();
;     grid.sync();
;     ...
;     for (int rep0 = 0; rep0 < REP_P0; ++rep0) {
;         PH_BEGIN
;         float* MOD = WSP(float, WS_MOD);
;         for (int it = bid; it < 192; it += G) {
;             const int l = it / 96, cb = it % 96;
;             LAS float* sc = (LAS float*)lds;
;             for (int idx = tid; idx < 24 * 1024; idx += 512) { const int b = idx >> 10, k = idx & 1023; const float c = b < 8 ? PIN(I_CP)[b * 1024 + k] : PIN(I_CS)[(b - 8) * 1024 + k]; sc[idx] = silu(c); }
;             __syncthreads();
;             const int cl0 = tid & 63, ks = tid >> 6;
;             float acc[24];
; #pragma unroll
;             for (int b = 0; b < 24; ++b) acc[b] = 0.f;
;             const float* wp = PIN(I_WADA) + (size_t)l * 1024 * 6144 + cb * 64 + cl0;
.LBB0_3:
	s_or_b64 exec, exec, s[2:3]
	v_lshrrev_b32_e32 v2, 20, v0
	v_lshrrev_b32_e32 v0, 10, v0
	v_or_b32_e32 v0, v0, v2
	v_and_or_b32 v0, v0, s8, v1
	v_cmp_eq_u32_e32 vcc, 0, v0
	s_waitcnt lgkmcnt(0)
	s_barrier
	s_barrier
.LBB0_13:
	s_or_b64 exec, exec, s[2:3]
	s_load_dwordx16 s[56:71], s[0:1], 0x0
	s_load_dwordx16 s[12:27], s[0:1], 0x40
	s_lshr_b32 s4, s10, 6
	s_barrier
	s_waitcnt lgkmcnt(0)
	v_mbcnt_lo_u32_b32 v0, -1, 0
	v_mbcnt_hi_u32_b32 v0, -1, v0
	v_writelane_b32 v253, s12, 0
	s_mov_b32 s6, s97
	s_mov_b64 s[8:9], s[90:91]
	v_writelane_b32 v253, s13, 1
	v_writelane_b32 v253, s14, 2
	v_writelane_b32 v253, s15, 3
	v_writelane_b32 v253, s16, 4
	v_writelane_b32 v253, s17, 5
	v_writelane_b32 v253, s18, 6
	v_writelane_b32 v253, s19, 7
	v_writelane_b32 v253, s20, 8
	v_writelane_b32 v253, s21, 9
	v_writelane_b32 v253, s22, 10
	v_writelane_b32 v253, s23, 11
	v_writelane_b32 v253, s24, 12
	v_writelane_b32 v253, s25, 13
	v_writelane_b32 v253, s26, 14
	v_writelane_b32 v253, s27, 15
	s_load_dwordx16 s[12:27], s[0:1], 0x80
	s_mov_b64 s[0:1], s[88:89]
	s_waitcnt lgkmcnt(0)
	v_writelane_b32 v253, s12, 16
	s_nop 1
	v_writelane_b32 v253, s13, 17
	v_writelane_b32 v253, s14, 18
	v_writelane_b32 v253, s15, 19
	v_writelane_b32 v253, s16, 20
	v_writelane_b32 v253, s17, 21
	v_writelane_b32 v253, s18, 22
	v_writelane_b32 v253, s19, 23
	v_writelane_b32 v253, s20, 24
	v_writelane_b32 v253, s21, 25
	v_writelane_b32 v253, s22, 26
	v_writelane_b32 v253, s23, 27
	v_writelane_b32 v253, s24, 28
	v_writelane_b32 v253, s25, 29
	v_writelane_b32 v253, s26, 30
	v_writelane_b32 v253, s27, 31
	v_writelane_b32 v253, s4, 32
	s_cmpk_lt_i32 s6, 0xc0
	v_lshl_add_u32 v12, s4, 6, v0
	v_ashrrev_i32_e32 v13, 31, v12
	s_cbranch_scc0 .LBB0_31
	v_and_b32_e32 v14, 63, v0
	s_add_u32 s10, s8, 0x2a4000
	v_ashrrev_i32_e32 v6, 6, v12
	v_mov_b32_e32 v17, 0
	v_lshlrev_b32_e32 v16, 2, v14
	s_addc_u32 s11, s9, 0
	s_lshl_b32 s4, s4, 8
	s_movk_i32 s7, 0x6000
	v_lshlrev_b32_e32 v1, 7, v6
	s_movk_i32 s5, 0x1800
	v_lshl_add_u64 v[4:5], s[8:9], 0, v[16:17]
	s_mov_b64 s[12:13], 0x4000
	s_add_i32 s4, s4, 0
	v_mul_lo_u32 v7, v6, s5
	v_lshl_add_u64 v[18:19], v[4:5], 0, s[12:13]
	v_or_b32_e32 v70, 0x70, v1
	v_lshl_add_u32 v71, v0, 2, s4
	v_add_u32_e32 v72, -16, v1
	v_mad_i64_i32 v[0:1], s[4:5], v1, s7, 0
	v_readlane_b32 s12, v253, 16
	v_or_b32_e32 v0, v0, v16
	v_readlane_b32 s26, v253, 30
	v_readlane_b32 s27, v253, 31
	v_mov_b32_e32 v2, s60
	v_mov_b32_e32 v3, s61
	v_add_u32_e32 v15, 0, v16
	s_movk_i32 s2, 0x600
	v_readlane_b32 s20, v253, 24
	v_readlane_b32 s21, v253, 25
	v_lshl_add_u64 v[0:1], s[26:27], 0, v[0:1]
	s_mov_b64 s[4:5], 0x5a000
	v_cmp_gt_i32_e64 s[0:1], s7, v12
	v_cmp_gt_i32_e64 s[2:3], s2, v12
	v_lshl_add_u64 v[20:21], v[12:13], 2, v[2:3]
	v_lshl_add_u64 v[22:23], v[0:1], 0, s[4:5]
	v_lshl_add_u32 v73, v6, 9, 0
	s_mov_b32 s26, 0xfffb2000
	s_mov_b32 s27, 0xfffb8000
	s_mov_b32 s28, 0xfffbe000
	s_mov_b32 s29, 0xfffc4000
	s_mov_b32 s30, 0xfffca000
	s_mov_b32 s31, 0xfffd0000
	s_mov_b32 s36, 0xfffd6000
	s_mov_b32 s37, 0xfffdc000
	s_mov_b32 s38, 0xfffe2000
	s_mov_b32 s39, 0xfffe8000
	s_mov_b32 s40, 0xfffee000
	s_mov_b32 s41, 0xffff4000
	s_movk_i32 s42, 0xa000
	s_mov_b64 s[20:21], 0x60000
	v_add_u32_e32 v74, v15, v7
	s_movk_i32 s43, 0x3ff
	s_mov_b32 s44, s6
	v_readlane_b32 s13, v253, 17
	v_readlane_b32 s14, v253, 18
	v_readlane_b32 s15, v253, 19
	v_readlane_b32 s16, v253, 20
	v_readlane_b32 s17, v253, 21
	v_readlane_b32 s18, v253, 22
	v_readlane_b32 s19, v253, 23
	v_readlane_b32 s22, v253, 26
	v_readlane_b32 s23, v253, 27
	v_readlane_b32 s24, v253, 28
	v_readlane_b32 s25, v253, 29
	s_branch .LBB0_16

; #define PG8_STAGE(bufoff, gbase, voff) do { _Pragma("unroll") for (int _i = 0; _i < 2; ++_i) \
;         __builtin_amdgcn_global_load_lds((const unsigned*)((const char*)(gbase) + (voff)[_i]), (LAS unsigned*)(lds + (bufoff) + ldsw + _i * 8192), 16, 0, 0); } while (0)
; #define PG8_LDA(dst, b, h) do { _Pragma("unroll") for (int m = 0; m < 4; ++m) _Pragma("unroll") for (int k = 0; k < 2; ++k) dst[m][k] = *(const LAS bf16x8*)(lds + PG8_SA(b, h) + aoff + m * 2048 + k * 1024); } while (0)
; #define PG8_LDB(dst, b, h) do { _Pragma("unroll") for (int n = 0; n < 2; ++n) _Pragma("unroll") for (int k = 0; k < 2; ++k) dst[n][k] = *(const LAS bf16x8*)(lds + PG8_SB(b, h) + boff + n * 2048 + k * 1024); } while (0)
; #define PG8_MMA(ai, bj, At, Bt) do { __builtin_amdgcn_s_setprio(1); _Pragma("unroll") for (int m = 0; m < 4; ++m) _Pragma("unroll") for (int n = 0; n < 2; ++n) _Pragma("unroll") for (int k = 0; k < 2; ++k) \
;         acc[ai][bj][m][n] = __builtin_amdgcn_mfma_f32_16x16x32_bf16(Bt[n][k], At[m][k], acc[ai][bj][m][n], 0, 0, 0); __builtin_amdgcn_s_setprio(0); } while (0)
; #define PG8_WAIT_V(n) asm volatile("s_waitcnt vmcnt(" #n ")" ::: "memory")
; #define PG8_WAIT_L(n) asm volatile("s_waitcnt lgkmcnt(" #n ")" ::: "memory")
; #define PG8_BAR __builtin_amdgcn_s_barrier()
; #define PG8_SCHED __builtin_amdgcn_sched_barrier(0)
; template <class Epi, bool ALIGN_EPI, bool SP2>
; DI void gemm_phase(int g_wave, LAS unsigned char* lds, const Gemm g, const StaticOrder& S, const Epi& E) {
;     ...
;             PG8_LDB(B0, 0, 0); PG8_LDB(B1, 0, 1); PG8_SCHED; PG8_LDA(At, 0, 0); PG8_STAGE(PG8_SA(1, 1), a1 + hstep, voffA);
;             PG8_WAIT_V(8); PG8_WAIT_L(0); PG8_BAR; PG8_MMA(0, 0, At, B0); PG8_MMA(0, 1, At, B1); PG8_BAR; PG8_SCHED;
;             PG8_LDA(At, 0, 1); PG8_STAGE(PG8_SB(0, 0), b2, voffB); PG8_STAGE(PG8_SB(0, 1), b2 + hstep, voffB); PG8_STAGE(PG8_SA(0, 0), a2, voffA);
;             PG8_WAIT_V(8); PG8_WAIT_L(0); PG8_BAR; PG8_MMA(1, 0, At, B0); PG8_MMA(1, 1, At, B1); PG8_BAR; PG8_SCHED;
.LBB0_251:
	s_add_u32 s30, s12, 0xfffc0080
	s_addc_u32 s31, s13, -1
	s_add_i32 s61, 0, 0x10000
	s_cmp_eq_u32 s60, 12
	s_cselect_b32 s35, s2, s31
	s_cselect_b32 s34, s17, s30
	v_add_u32_e32 v128, s61, v147
	s_cselect_b32 s31, s23, s59
	s_cselect_b32 s30, s25, s58
	s_add_i32 s64, 0, 0x14000
	ds_read_b128 v[150:153], v128
	ds_read_b128 v[154:157], v128 offset:1024
	ds_read_b128 v[158:161], v128 offset:2048
	ds_read_b128 v[162:165], v128 offset:3072
	v_add_u32_e32 v128, s64, v147
	ds_read_b128 v[166:169], v128
	ds_read_b128 v[170:173], v128 offset:1024
	ds_read_b128 v[174:177], v128 offset:2048
	ds_read_b128 v[178:181], v128 offset:3072
	v_lshl_add_u64 v[144:145], s[12:13], 0, v[138:139]
	s_add_i32 m0, s43, 0xc000
	ds_read_b128 v[182:185], v148
	ds_read_b128 v[186:189], v148 offset:1024
	ds_read_b128 v[190:193], v148 offset:2048
	ds_read_b128 v[194:197], v148 offset:3072
	ds_read_b128 v[198:201], v148 offset:4096
	ds_read_b128 v[202:205], v148 offset:5120
	ds_read_b128 v[206:209], v148 offset:6144
	ds_read_b128 v[210:213], v148 offset:7168
	global_load_lds_dwordx4 v[144:145], off
	v_lshl_add_u64 v[144:145], s[12:13], 0, v[140:141]
	s_add_i32 m0, s43, 0xe000
	s_nop 0
	global_load_lds_dwordx4 v[144:145], off
	s_waitcnt vmcnt(8)
	s_waitcnt lgkmcnt(0)
	s_barrier
	s_setprio 1
	s_waitcnt lgkmcnt(0)
	v_mfma_f32_16x16x32_bf16 v[124:127], v[150:153], v[182:185], v[124:127]
	v_mfma_f32_16x16x32_bf16 v[120:123], v[158:161], v[182:185], v[120:123]
	v_mfma_f32_16x16x32_bf16 v[116:119], v[150:153], v[190:193], v[116:119]
	v_mfma_f32_16x16x32_bf16 v[112:115], v[158:161], v[190:193], v[112:115]
	v_mfma_f32_16x16x32_bf16 v[100:103], v[150:153], v[198:201], v[100:103]
	v_mfma_f32_16x16x32_bf16 v[96:99], v[158:161], v[198:201], v[96:99]
	v_mfma_f32_16x16x32_bf16 v[84:87], v[150:153], v[206:209], v[84:87]
	v_mfma_f32_16x16x32_bf16 v[80:83], v[158:161], v[206:209], v[80:83]
	v_mfma_f32_16x16x32_bf16 v[124:127], v[154:157], v[186:189], v[124:127]
	v_mfma_f32_16x16x32_bf16 v[120:123], v[162:165], v[186:189], v[120:123]
	v_mfma_f32_16x16x32_bf16 v[116:119], v[154:157], v[194:197], v[116:119]
	v_mfma_f32_16x16x32_bf16 v[112:115], v[162:165], v[194:197], v[112:115]
	v_mfma_f32_16x16x32_bf16 v[100:103], v[154:157], v[202:205], v[100:103]
	v_mfma_f32_16x16x32_bf16 v[96:99], v[162:165], v[202:205], v[96:99]
	v_mfma_f32_16x16x32_bf16 v[84:87], v[154:157], v[210:213], v[84:87]
	v_mfma_f32_16x16x32_bf16 v[80:83], v[162:165], v[210:213], v[80:83]
	s_setprio 0
	s_setprio 1
	v_mfma_f32_16x16x32_bf16 v[108:111], v[166:169], v[182:185], v[108:111]
	v_mfma_f32_16x16x32_bf16 v[104:107], v[174:177], v[182:185], v[104:107]
	v_mfma_f32_16x16x32_bf16 v[92:95], v[166:169], v[190:193], v[92:95]
	v_mfma_f32_16x16x32_bf16 v[88:91], v[174:177], v[190:193], v[88:91]
	v_mfma_f32_16x16x32_bf16 v[76:79], v[166:169], v[198:201], v[76:79]
	v_mfma_f32_16x16x32_bf16 v[72:75], v[174:177], v[198:201], v[72:75]
	v_mfma_f32_16x16x32_bf16 v[68:71], v[166:169], v[206:209], v[68:71]
	v_mfma_f32_16x16x32_bf16 v[64:67], v[174:177], v[206:209], v[64:67]
	v_mfma_f32_16x16x32_bf16 v[108:111], v[170:173], v[186:189], v[108:111]
	v_mfma_f32_16x16x32_bf16 v[104:107], v[178:181], v[186:189], v[104:107]
	v_mfma_f32_16x16x32_bf16 v[92:95], v[170:173], v[194:197], v[92:95]
	v_mfma_f32_16x16x32_bf16 v[88:91], v[178:181], v[194:197], v[88:91]
	v_mfma_f32_16x16x32_bf16 v[76:79], v[170:173], v[202:205], v[76:79]
	v_mfma_f32_16x16x32_bf16 v[72:75], v[178:181], v[202:205], v[72:75]
	v_mfma_f32_16x16x32_bf16 v[68:71], v[170:173], v[210:213], v[68:71]
	v_mfma_f32_16x16x32_bf16 v[64:67], v[178:181], v[210:213], v[64:67]
	s_setprio 0
	s_barrier
	s_add_i32 s61, s61, s42
	v_lshl_add_u64 v[144:145], s[30:31], 0, v[132:133]
	s_mov_b32 m0, s61
	global_load_lds_dwordx4 v[144:145], off
	s_add_i32 m0, s61, 0x2000
	s_add_u32 s62, s30, 0x40000
	v_lshl_add_u64 v[214:215], s[30:31], 0, v[136:137]
	s_addc_u32 s63, s31, 0
	s_add_i32 s61, s64, s42
	global_load_lds_dwordx4 v[214:215], off
	v_lshl_add_u64 v[216:217], s[62:63], 0, v[132:133]
	s_mov_b32 m0, s61
	v_lshl_add_u64 v[218:219], s[34:35], 0, v[134:135]
	global_load_lds_dwordx4 v[216:217], off
	v_lshl_add_u64 v[216:217], s[62:63], 0, v[136:137]
	s_add_i32 m0, s61, 0x2000
	s_nop 0
	global_load_lds_dwordx4 v[216:217], off
	v_lshl_add_u64 v[216:217], s[34:35], 0, v[130:131]
	s_mov_b32 m0, s43
	s_nop 0
	global_load_lds_dwordx4 v[216:217], off
	s_mov_b32 m0, s44
	s_nop 0
	global_load_lds_dwordx4 v[218:219], off
	s_waitcnt vmcnt(8)
	s_waitcnt lgkmcnt(0)
	s_barrier
	s_setprio 1
	s_waitcnt lgkmcnt(0)
	s_setprio 0
	s_setprio 1
	s_setprio 0
	s_barrier
; #define PG8_STAGE(bufoff, gbase, voff) do { _Pragma("unroll") for (int _i = 0; _i < 2; ++_i) \
;         __builtin_amdgcn_global_load_lds((const unsigned*)((const char*)(gbase) + (voff)[_i]), (LAS unsigned*)(lds + (bufoff) + ldsw + _i * 8192), 16, 0, 0); } while (0)
; #define PG8_LDA(dst, b, h) do { _Pragma("unroll") for (int m = 0; m < 4; ++m) _Pragma("unroll") for (int k = 0; k < 2; ++k) dst[m][k] = *(const LAS bf16x8*)(lds + PG8_SA(b, h) + aoff + m * 2048 + k * 1024); } while (0)
; #define PG8_LDB(dst, b, h) do { _Pragma("unroll") for (int n = 0; n < 2; ++n) _Pragma("unroll") for (int k = 0; k < 2; ++k) dst[n][k] = *(const LAS bf16x8*)(lds + PG8_SB(b, h) + boff + n * 2048 + k * 1024); } while (0)
; #define PG8_MMA(ai, bj, At, Bt) do { __builtin_amdgcn_s_setprio(1); _Pragma("unroll") for (int m = 0; m < 4; ++m) _Pragma("unroll") for (int n = 0; n < 2; ++n) _Pragma("unroll") for (int k = 0; k < 2; ++k) \
;         acc[ai][bj][m][n] = __builtin_amdgcn_mfma_f32_16x16x32_bf16(Bt[n][k], At[m][k], acc[ai][bj][m][n], 0, 0, 0); __builtin_amdgcn_s_setprio(0); } while (0)
; #define PG8_WAIT_V(n) asm volatile("s_waitcnt vmcnt(" #n ")" ::: "memory")
; #define PG8_WAIT_L(n) asm volatile("s_waitcnt lgkmcnt(" #n ")" ::: "memory")
; #define PG8_BAR __builtin_amdgcn_s_barrier()
; #define PG8_SCHED __builtin_amdgcn_sched_barrier(0)
; template <class Epi, bool ALIGN_EPI, bool SP2>
; DI void gemm_phase(int g_wave, LAS unsigned char* lds, const Gemm g, const StaticOrder& S, const Epi& E) {
;     ...
;             PG8_LDB(B0, 1, 0); PG8_LDB(B1, 1, 1); PG8_SCHED; PG8_LDA(At, 1, 0); PG8_STAGE(PG8_SA(0, 1), a2 + hstep, voffA);
;             PG8_WAIT_V(8); PG8_WAIT_L(0); PG8_BAR; PG8_MMA(0, 0, At, B0); PG8_MMA(0, 1, At, B1); PG8_BAR; PG8_SCHED;
;             PG8_LDA(At, 1, 1); PG8_STAGE(PG8_SB(1, 0), b3, voffB); PG8_STAGE(PG8_SB(1, 1), b3 + hstep, voffB); PG8_STAGE(PG8_SA(1, 0), a3, voffA);
;             PG8_WAIT_V(8); PG8_WAIT_L(0); PG8_BAR; PG8_MMA(1, 0, At, B0); PG8_MMA(1, 1, At, B1); PG8_BAR; PG8_SCHED;
	s_add_i32 s61, 0, 0x18000
	v_add_u32_e32 v128, s61, v147
	s_add_i32 s62, 0, 0x1c000
	ds_read_b128 v[150:153], v128
	ds_read_b128 v[154:157], v128 offset:1024
	ds_read_b128 v[158:161], v128 offset:2048
	ds_read_b128 v[162:165], v128 offset:3072
	v_add_u32_e32 v128, s62, v147
	ds_read_b128 v[166:169], v128
	ds_read_b128 v[170:173], v128 offset:1024
	ds_read_b128 v[174:177], v128 offset:2048
	ds_read_b128 v[178:181], v128 offset:3072
	s_add_u32 s34, s34, 0x40000
	s_addc_u32 s35, s35, 0
	s_mov_b32 m0, s45
	v_lshl_add_u64 v[220:221], s[34:35], 0, v[130:131]
	ds_read_b128 v[182:185], v148 offset:32768
	ds_read_b128 v[186:189], v148 offset:33792
	ds_read_b128 v[190:193], v148 offset:34816
	ds_read_b128 v[194:197], v148 offset:35840
	ds_read_b128 v[198:201], v148 offset:36864
	ds_read_b128 v[202:205], v148 offset:37888
	ds_read_b128 v[206:209], v148 offset:38912
	ds_read_b128 v[210:213], v148 offset:39936
	global_load_lds_dwordx4 v[220:221], off
	v_lshl_add_u64 v[220:221], s[34:35], 0, v[134:135]
	s_mov_b32 m0, s46
	s_nop 0
	global_load_lds_dwordx4 v[220:221], off
	s_waitcnt vmcnt(8)
	s_waitcnt lgkmcnt(0)
	s_barrier
	s_setprio 1
	s_waitcnt lgkmcnt(0)
	v_mfma_f32_16x16x32_bf16 v[124:127], v[150:153], v[182:185], v[124:127]
	v_mfma_f32_16x16x32_bf16 v[120:123], v[158:161], v[182:185], v[120:123]
	v_mfma_f32_16x16x32_bf16 v[116:119], v[150:153], v[190:193], v[116:119]
	v_mfma_f32_16x16x32_bf16 v[112:115], v[158:161], v[190:193], v[112:115]
	v_mfma_f32_16x16x32_bf16 v[100:103], v[150:153], v[198:201], v[100:103]
	v_mfma_f32_16x16x32_bf16 v[96:99], v[158:161], v[198:201], v[96:99]
	v_mfma_f32_16x16x32_bf16 v[84:87], v[150:153], v[206:209], v[84:87]
	v_mfma_f32_16x16x32_bf16 v[80:83], v[158:161], v[206:209], v[80:83]
	v_mfma_f32_16x16x32_bf16 v[124:127], v[154:157], v[186:189], v[124:127]
	v_mfma_f32_16x16x32_bf16 v[120:123], v[162:165], v[186:189], v[120:123]
	v_mfma_f32_16x16x32_bf16 v[116:119], v[154:157], v[194:197], v[116:119]
	v_mfma_f32_16x16x32_bf16 v[112:115], v[162:165], v[194:197], v[112:115]
	v_mfma_f32_16x16x32_bf16 v[100:103], v[154:157], v[202:205], v[100:103]
	v_mfma_f32_16x16x32_bf16 v[96:99], v[162:165], v[202:205], v[96:99]
	v_mfma_f32_16x16x32_bf16 v[84:87], v[154:157], v[210:213], v[84:87]
	v_mfma_f32_16x16x32_bf16 v[80:83], v[162:165], v[210:213], v[80:83]
	s_setprio 0
	s_setprio 1
	v_mfma_f32_16x16x32_bf16 v[108:111], v[166:169], v[182:185], v[108:111]
	v_mfma_f32_16x16x32_bf16 v[104:107], v[174:177], v[182:185], v[104:107]
	v_mfma_f32_16x16x32_bf16 v[92:95], v[166:169], v[190:193], v[92:95]
	v_mfma_f32_16x16x32_bf16 v[88:91], v[174:177], v[190:193], v[88:91]
	v_mfma_f32_16x16x32_bf16 v[76:79], v[166:169], v[198:201], v[76:79]
	v_mfma_f32_16x16x32_bf16 v[72:75], v[174:177], v[198:201], v[72:75]
	v_mfma_f32_16x16x32_bf16 v[68:71], v[166:169], v[206:209], v[68:71]
	v_mfma_f32_16x16x32_bf16 v[64:67], v[174:177], v[206:209], v[64:67]
	v_mfma_f32_16x16x32_bf16 v[108:111], v[170:173], v[186:189], v[108:111]
	v_mfma_f32_16x16x32_bf16 v[104:107], v[178:181], v[186:189], v[104:107]
	v_mfma_f32_16x16x32_bf16 v[92:95], v[170:173], v[194:197], v[92:95]
	v_mfma_f32_16x16x32_bf16 v[88:91], v[178:181], v[194:197], v[88:91]
	v_mfma_f32_16x16x32_bf16 v[76:79], v[170:173], v[202:205], v[76:79]
	v_mfma_f32_16x16x32_bf16 v[72:75], v[178:181], v[202:205], v[72:75]
	v_mfma_f32_16x16x32_bf16 v[68:71], v[170:173], v[210:213], v[68:71]
	v_mfma_f32_16x16x32_bf16 v[64:67], v[178:181], v[210:213], v[64:67]
	s_setprio 0
	s_barrier
	s_add_i32 s34, s61, s42
	v_lshl_add_u64 v[144:145], v[144:145], 0, s[4:5]
	s_mov_b32 m0, s34
	global_load_lds_dwordx4 v[144:145], off
	s_add_i32 m0, s34, 0x2000
	s_add_u32 s30, s30, 0x40080
	v_lshl_add_u64 v[144:145], v[214:215], 0, s[4:5]
	s_addc_u32 s31, s31, 0
	s_add_i32 s34, s62, s42
	global_load_lds_dwordx4 v[144:145], off
	v_lshl_add_u64 v[144:145], s[30:31], 0, v[132:133]
	s_mov_b32 m0, s34
	s_nop 0
	global_load_lds_dwordx4 v[144:145], off
	v_lshl_add_u64 v[144:145], s[30:31], 0, v[136:137]
	s_add_i32 m0, s34, 0x2000
	s_nop 0
	global_load_lds_dwordx4 v[144:145], off
	v_lshl_add_u64 v[144:145], v[216:217], 0, s[4:5]
	s_mov_b32 m0, s50
	s_nop 0
	global_load_lds_dwordx4 v[144:145], off
	v_lshl_add_u64 v[144:145], v[218:219], 0, s[4:5]
	s_mov_b32 m0, s51
	s_nop 0
	global_load_lds_dwordx4 v[144:145], off
	s_waitcnt vmcnt(8)
	s_waitcnt lgkmcnt(0)
	s_barrier
	s_setprio 1
	s_waitcnt lgkmcnt(0)
	s_setprio 0
	s_setprio 1
	s_setprio 0
	s_barrier
	s_add_i32 s60, s60, 2
	s_add_u32 s12, s12, 0x100
	s_addc_u32 s13, s13, 0
	s_add_u32 s58, s58, 0x100
	s_addc_u32 s59, s59, 0
	s_cmp_gt_u32 s60, 13
	s_cbranch_scc0 .LBB0_251
	s_and_b64 vcc, exec, s[18:19]
	s_cbranch_vccz .LBB0_254
	s_barrier

; #define PG8_STAGE(bufoff, gbase, voff) do { _Pragma("unroll") for (int _i = 0; _i < 2; ++_i) \
;         __builtin_amdgcn_global_load_lds((const unsigned*)((const char*)(gbase) + (voff)[_i]), (LAS unsigned*)(lds + (bufoff) + ldsw + _i * 8192), 16, 0, 0); } while (0)
; #define PG8_LDA(dst, b, h) do { _Pragma("unroll") for (int m = 0; m < 4; ++m) _Pragma("unroll") for (int k = 0; k < 2; ++k) dst[m][k] = *(const LAS bf16x8*)(lds + PG8_SA(b, h) + aoff + m * 2048 + k * 1024); } while (0)
; #define PG8_LDB(dst, b, h) do { _Pragma("unroll") for (int n = 0; n < 2; ++n) _Pragma("unroll") for (int k = 0; k < 2; ++k) dst[n][k] = *(const LAS bf16x8*)(lds + PG8_SB(b, h) + boff + n * 2048 + k * 1024); } while (0)
; #define PG8_MMA(ai, bj, At, Bt) do { __builtin_amdgcn_s_setprio(1); _Pragma("unroll") for (int m = 0; m < 4; ++m) _Pragma("unroll") for (int n = 0; n < 2; ++n) _Pragma("unroll") for (int k = 0; k < 2; ++k) \
;         acc[ai][bj][m][n] = __builtin_amdgcn_mfma_f32_16x16x32_bf16(Bt[n][k], At[m][k], acc[ai][bj][m][n], 0, 0, 0); __builtin_amdgcn_s_setprio(0); } while (0)
; #define PG8_WAIT_V(n) asm volatile("s_waitcnt vmcnt(" #n ")" ::: "memory")
; #define PG8_WAIT_L(n) asm volatile("s_waitcnt lgkmcnt(" #n ")" ::: "memory")
; #define PG8_BAR __builtin_amdgcn_s_barrier()
; #define PG8_SCHED __builtin_amdgcn_sched_barrier(0)
; template <class Epi, bool ALIGN_EPI, bool SP2>
; DI void gemm_phase(int g_wave, LAS unsigned char* lds, const Gemm g, const StaticOrder& S, const Epi& E) {
;     ...
;             PG8_LDB(B0, 0, 0); PG8_LDB(B1, 0, 1); PG8_SCHED; PG8_LDA(At, 0, 0); PG8_STAGE(PG8_SA(1, 1), a1 + hstep, voffA);
;             PG8_WAIT_V(8); PG8_WAIT_L(0); PG8_BAR; PG8_MMA(0, 0, At, B0); PG8_MMA(0, 1, At, B1); PG8_BAR; PG8_SCHED;
;             PG8_LDA(At, 0, 1); PG8_STAGE(PG8_SB(0, 0), b2, voffB); PG8_STAGE(PG8_SB(0, 1), b2 + hstep, voffB); PG8_STAGE(PG8_SA(0, 0), a2, voffA);
;             PG8_WAIT_V(8); PG8_WAIT_L(0); PG8_BAR; PG8_MMA(1, 0, At, B0); PG8_MMA(1, 1, At, B1); PG8_BAR; PG8_SCHED;
.LBB0_1638:
	s_add_u32 s34, s12, 0xfffc0080
	s_addc_u32 s35, s13, -1
	s_add_i32 s72, 0, 0x10000
	s_cmp_eq_u32 s71, 12
	s_cselect_b32 s37, s17, s35
	s_cselect_b32 s36, s27, s34
	v_add_u32_e32 v140, s72, v142
	s_cselect_b32 s35, s25, s70
	s_cselect_b32 s34, s66, s67
	s_add_i32 s74, 0, 0x14000
	ds_read_b128 v[144:147], v140
	ds_read_b128 v[148:151], v140 offset:1024
	ds_read_b128 v[152:155], v140 offset:2048
	ds_read_b128 v[156:159], v140 offset:3072
	v_add_u32_e32 v140, s74, v142
	ds_read_b128 v[160:163], v140
	ds_read_b128 v[164:167], v140 offset:1024
	ds_read_b128 v[168:171], v140 offset:2048
	ds_read_b128 v[172:175], v140 offset:3072
	v_lshl_add_u64 v[140:141], s[12:13], 0, v[136:137]
	s_add_i32 m0, s47, 0xc000
	ds_read_b128 v[176:179], v143
	ds_read_b128 v[180:183], v143 offset:1024
	ds_read_b128 v[184:187], v143 offset:2048
	ds_read_b128 v[188:191], v143 offset:3072
	ds_read_b128 v[192:195], v143 offset:4096
	ds_read_b128 v[196:199], v143 offset:5120
	ds_read_b128 v[200:203], v143 offset:6144
	ds_read_b128 v[204:207], v143 offset:7168
	global_load_lds_dwordx4 v[140:141], off
	v_lshl_add_u64 v[140:141], s[12:13], 0, v[138:139]
	s_add_i32 m0, s47, 0xe000
	s_nop 0
	global_load_lds_dwordx4 v[140:141], off
	s_waitcnt vmcnt(8)
	s_waitcnt lgkmcnt(0)
	s_barrier
	s_setprio 1
	s_waitcnt lgkmcnt(0)
	v_mfma_f32_16x16x32_bf16 v[124:127], v[144:147], v[176:179], v[124:127]
	v_mfma_f32_16x16x32_bf16 v[120:123], v[152:155], v[176:179], v[120:123]
	v_mfma_f32_16x16x32_bf16 v[116:119], v[144:147], v[184:187], v[116:119]
	v_mfma_f32_16x16x32_bf16 v[108:111], v[152:155], v[184:187], v[108:111]
	v_mfma_f32_16x16x32_bf16 v[100:103], v[144:147], v[192:195], v[100:103]
	v_mfma_f32_16x16x32_bf16 v[96:99], v[152:155], v[192:195], v[96:99]
	v_mfma_f32_16x16x32_bf16 v[84:87], v[144:147], v[200:203], v[84:87]
	v_mfma_f32_16x16x32_bf16 v[80:83], v[152:155], v[200:203], v[80:83]
	v_mfma_f32_16x16x32_bf16 v[124:127], v[148:151], v[180:183], v[124:127]
	v_mfma_f32_16x16x32_bf16 v[120:123], v[156:159], v[180:183], v[120:123]
	v_mfma_f32_16x16x32_bf16 v[116:119], v[148:151], v[188:191], v[116:119]
	v_mfma_f32_16x16x32_bf16 v[108:111], v[156:159], v[188:191], v[108:111]
	v_mfma_f32_16x16x32_bf16 v[100:103], v[148:151], v[196:199], v[100:103]
	v_mfma_f32_16x16x32_bf16 v[96:99], v[156:159], v[196:199], v[96:99]
	v_mfma_f32_16x16x32_bf16 v[84:87], v[148:151], v[204:207], v[84:87]
	v_mfma_f32_16x16x32_bf16 v[80:83], v[156:159], v[204:207], v[80:83]
	s_setprio 0
	s_setprio 1
	v_mfma_f32_16x16x32_bf16 v[112:115], v[160:163], v[176:179], v[112:115]
	v_mfma_f32_16x16x32_bf16 v[104:107], v[168:171], v[176:179], v[104:107]
	v_mfma_f32_16x16x32_bf16 v[92:95], v[160:163], v[184:187], v[92:95]
	v_mfma_f32_16x16x32_bf16 v[88:91], v[168:171], v[184:187], v[88:91]
	v_mfma_f32_16x16x32_bf16 v[76:79], v[160:163], v[192:195], v[76:79]
	v_mfma_f32_16x16x32_bf16 v[72:75], v[168:171], v[192:195], v[72:75]
	v_mfma_f32_16x16x32_bf16 v[68:71], v[160:163], v[200:203], v[68:71]
	v_mfma_f32_16x16x32_bf16 v[64:67], v[168:171], v[200:203], v[64:67]
	v_mfma_f32_16x16x32_bf16 v[112:115], v[164:167], v[180:183], v[112:115]
	v_mfma_f32_16x16x32_bf16 v[104:107], v[172:175], v[180:183], v[104:107]
	v_mfma_f32_16x16x32_bf16 v[92:95], v[164:167], v[188:191], v[92:95]
	v_mfma_f32_16x16x32_bf16 v[88:91], v[172:175], v[188:191], v[88:91]
	v_mfma_f32_16x16x32_bf16 v[76:79], v[164:167], v[196:199], v[76:79]
	v_mfma_f32_16x16x32_bf16 v[72:75], v[172:175], v[196:199], v[72:75]
	v_mfma_f32_16x16x32_bf16 v[68:71], v[164:167], v[204:207], v[68:71]
	v_mfma_f32_16x16x32_bf16 v[64:67], v[172:175], v[204:207], v[64:67]
	s_setprio 0
	s_barrier
	s_add_i32 s72, s72, s46
	v_lshl_add_u64 v[140:141], s[34:35], 0, v[130:131]
	s_mov_b32 m0, s72
	global_load_lds_dwordx4 v[140:141], off
	s_add_i32 m0, s72, 0x2000
	s_add_u32 s72, s34, 0x40000
	v_lshl_add_u64 v[208:209], s[34:35], 0, v[134:135]
	s_addc_u32 s73, s35, 0
	s_add_i32 s74, s74, s46
	global_load_lds_dwordx4 v[208:209], off
	v_lshl_add_u64 v[210:211], s[72:73], 0, v[130:131]
	s_mov_b32 m0, s74
	v_lshl_add_u64 v[212:213], s[36:37], 0, v[132:133]
	global_load_lds_dwordx4 v[210:211], off
	v_lshl_add_u64 v[210:211], s[72:73], 0, v[134:135]
	s_add_i32 m0, s74, 0x2000
	s_nop 0
	global_load_lds_dwordx4 v[210:211], off
	v_lshl_add_u64 v[210:211], s[36:37], 0, v[128:129]
	s_mov_b32 m0, s47
	s_nop 0
	global_load_lds_dwordx4 v[210:211], off
	s_mov_b32 m0, s49
	s_nop 0
	global_load_lds_dwordx4 v[212:213], off
	s_waitcnt vmcnt(8)
	s_waitcnt lgkmcnt(0)
	s_barrier
	s_setprio 1
	s_waitcnt lgkmcnt(0)
	s_setprio 0
	s_setprio 1
	s_setprio 0
	s_barrier
; #define PG8_STAGE(bufoff, gbase, voff) do { _Pragma("unroll") for (int _i = 0; _i < 2; ++_i) \
;         __builtin_amdgcn_global_load_lds((const unsigned*)((const char*)(gbase) + (voff)[_i]), (LAS unsigned*)(lds + (bufoff) + ldsw + _i * 8192), 16, 0, 0); } while (0)
; #define PG8_LDA(dst, b, h) do { _Pragma("unroll") for (int m = 0; m < 4; ++m) _Pragma("unroll") for (int k = 0; k < 2; ++k) dst[m][k] = *(const LAS bf16x8*)(lds + PG8_SA(b, h) + aoff + m * 2048 + k * 1024); } while (0)
; #define PG8_LDB(dst, b, h) do { _Pragma("unroll") for (int n = 0; n < 2; ++n) _Pragma("unroll") for (int k = 0; k < 2; ++k) dst[n][k] = *(const LAS bf16x8*)(lds + PG8_SB(b, h) + boff + n * 2048 + k * 1024); } while (0)
; #define PG8_MMA(ai, bj, At, Bt) do { __builtin_amdgcn_s_setprio(1); _Pragma("unroll") for (int m = 0; m < 4; ++m) _Pragma("unroll") for (int n = 0; n < 2; ++n) _Pragma("unroll") for (int k = 0; k < 2; ++k) \
;         acc[ai][bj][m][n] = __builtin_amdgcn_mfma_f32_16x16x32_bf16(Bt[n][k], At[m][k], acc[ai][bj][m][n], 0, 0, 0); __builtin_amdgcn_s_setprio(0); } while (0)
; #define PG8_WAIT_V(n) asm volatile("s_waitcnt vmcnt(" #n ")" ::: "memory")
; #define PG8_WAIT_L(n) asm volatile("s_waitcnt lgkmcnt(" #n ")" ::: "memory")
; #define PG8_BAR __builtin_amdgcn_s_barrier()
; #define PG8_SCHED __builtin_amdgcn_sched_barrier(0)
; template <class Epi, bool ALIGN_EPI, bool SP2>
; DI void gemm_phase(int g_wave, LAS unsigned char* lds, const Gemm g, const StaticOrder& S, const Epi& E) {
;     ...
;             PG8_LDB(B0, 1, 0); PG8_LDB(B1, 1, 1); PG8_SCHED; PG8_LDA(At, 1, 0); PG8_STAGE(PG8_SA(0, 1), a2 + hstep, voffA);
;             PG8_WAIT_V(8); PG8_WAIT_L(0); PG8_BAR; PG8_MMA(0, 0, At, B0); PG8_MMA(0, 1, At, B1); PG8_BAR; PG8_SCHED;
;             PG8_LDA(At, 1, 1); PG8_STAGE(PG8_SB(1, 0), b3, voffB); PG8_STAGE(PG8_SB(1, 1), b3 + hstep, voffB); PG8_STAGE(PG8_SA(1, 0), a3, voffA);
;             PG8_WAIT_V(8); PG8_WAIT_L(0); PG8_BAR; PG8_MMA(1, 0, At, B0); PG8_MMA(1, 1, At, B1); PG8_BAR; PG8_SCHED;
	s_add_i32 s72, 0, 0x18000
	s_add_i32 s73, 0, 0x1c000
	v_add_u32_e32 v156, s72, v142
	v_add_u32_e32 v172, s73, v142
	ds_read_b128 v[144:147], v156
	ds_read_b128 v[148:151], v156 offset:1024
	ds_read_b128 v[152:155], v156 offset:2048
	ds_read_b128 v[156:159], v156 offset:3072
	ds_read_b128 v[160:163], v172
	ds_read_b128 v[164:167], v172 offset:1024
	ds_read_b128 v[168:171], v172 offset:2048
	ds_read_b128 v[172:175], v172 offset:3072
	s_add_u32 s36, s36, 0x40000
	s_addc_u32 s37, s37, 0
	s_mov_b32 m0, s52
	v_lshl_add_u64 v[214:215], s[36:37], 0, v[128:129]
	ds_read_b128 v[176:179], v143 offset:32768
	ds_read_b128 v[180:183], v143 offset:33792
	ds_read_b128 v[184:187], v143 offset:34816
	ds_read_b128 v[188:191], v143 offset:35840
	ds_read_b128 v[192:195], v143 offset:36864
	ds_read_b128 v[196:199], v143 offset:37888
	ds_read_b128 v[200:203], v143 offset:38912
	ds_read_b128 v[204:207], v143 offset:39936
	global_load_lds_dwordx4 v[214:215], off
	v_lshl_add_u64 v[214:215], s[36:37], 0, v[132:133]
	s_mov_b32 m0, s53
	s_nop 0
	global_load_lds_dwordx4 v[214:215], off
	s_waitcnt vmcnt(8)
	s_waitcnt lgkmcnt(0)
	s_barrier
	s_setprio 1
	s_waitcnt lgkmcnt(0)
	v_mfma_f32_16x16x32_bf16 v[124:127], v[144:147], v[176:179], v[124:127]
	v_mfma_f32_16x16x32_bf16 v[120:123], v[152:155], v[176:179], v[120:123]
	v_mfma_f32_16x16x32_bf16 v[116:119], v[144:147], v[184:187], v[116:119]
	v_mfma_f32_16x16x32_bf16 v[108:111], v[152:155], v[184:187], v[108:111]
	v_mfma_f32_16x16x32_bf16 v[100:103], v[144:147], v[192:195], v[100:103]
	v_mfma_f32_16x16x32_bf16 v[96:99], v[152:155], v[192:195], v[96:99]
	v_mfma_f32_16x16x32_bf16 v[84:87], v[144:147], v[200:203], v[84:87]
	v_mfma_f32_16x16x32_bf16 v[80:83], v[152:155], v[200:203], v[80:83]
	v_mfma_f32_16x16x32_bf16 v[124:127], v[148:151], v[180:183], v[124:127]
	v_mfma_f32_16x16x32_bf16 v[120:123], v[156:159], v[180:183], v[120:123]
	v_mfma_f32_16x16x32_bf16 v[116:119], v[148:151], v[188:191], v[116:119]
	v_mfma_f32_16x16x32_bf16 v[108:111], v[156:159], v[188:191], v[108:111]
	v_mfma_f32_16x16x32_bf16 v[100:103], v[148:151], v[196:199], v[100:103]
	v_mfma_f32_16x16x32_bf16 v[96:99], v[156:159], v[196:199], v[96:99]
	v_mfma_f32_16x16x32_bf16 v[84:87], v[148:151], v[204:207], v[84:87]
	v_mfma_f32_16x16x32_bf16 v[80:83], v[156:159], v[204:207], v[80:83]
	s_setprio 0
	s_setprio 1
	v_mfma_f32_16x16x32_bf16 v[112:115], v[160:163], v[176:179], v[112:115]
	v_mfma_f32_16x16x32_bf16 v[104:107], v[168:171], v[176:179], v[104:107]
	v_mfma_f32_16x16x32_bf16 v[92:95], v[160:163], v[184:187], v[92:95]
	v_mfma_f32_16x16x32_bf16 v[88:91], v[168:171], v[184:187], v[88:91]
	v_mfma_f32_16x16x32_bf16 v[76:79], v[160:163], v[192:195], v[76:79]
	v_mfma_f32_16x16x32_bf16 v[72:75], v[168:171], v[192:195], v[72:75]
	v_mfma_f32_16x16x32_bf16 v[68:71], v[160:163], v[200:203], v[68:71]
	v_mfma_f32_16x16x32_bf16 v[64:67], v[168:171], v[200:203], v[64:67]
	v_mfma_f32_16x16x32_bf16 v[112:115], v[164:167], v[180:183], v[112:115]
	v_mfma_f32_16x16x32_bf16 v[104:107], v[172:175], v[180:183], v[104:107]
	v_mfma_f32_16x16x32_bf16 v[92:95], v[164:167], v[188:191], v[92:95]
	v_mfma_f32_16x16x32_bf16 v[88:91], v[172:175], v[188:191], v[88:91]
	v_mfma_f32_16x16x32_bf16 v[76:79], v[164:167], v[196:199], v[76:79]
	v_mfma_f32_16x16x32_bf16 v[72:75], v[172:175], v[196:199], v[72:75]
	v_mfma_f32_16x16x32_bf16 v[68:71], v[164:167], v[204:207], v[68:71]
	v_mfma_f32_16x16x32_bf16 v[64:67], v[172:175], v[204:207], v[64:67]
	s_setprio 0
	s_barrier
	s_add_i32 s36, s72, s46
	v_lshl_add_u64 v[140:141], v[140:141], 0, s[68:69]
	s_mov_b32 m0, s36
	global_load_lds_dwordx4 v[140:141], off
	s_add_i32 m0, s36, 0x2000
	s_add_u32 s34, s34, 0x40080
	v_lshl_add_u64 v[140:141], v[208:209], 0, s[68:69]
	s_addc_u32 s35, s35, 0
	s_add_i32 s36, s73, s46
	global_load_lds_dwordx4 v[140:141], off
	v_lshl_add_u64 v[140:141], s[34:35], 0, v[130:131]
	s_mov_b32 m0, s36
	s_nop 0
	global_load_lds_dwordx4 v[140:141], off
	v_lshl_add_u64 v[140:141], s[34:35], 0, v[134:135]
	s_add_i32 m0, s36, 0x2000
	s_nop 0
	global_load_lds_dwordx4 v[140:141], off
	v_lshl_add_u64 v[140:141], v[210:211], 0, s[68:69]
	s_mov_b32 m0, s56
	s_nop 0
	global_load_lds_dwordx4 v[140:141], off
	v_lshl_add_u64 v[140:141], v[212:213], 0, s[68:69]
	s_mov_b32 m0, s57
	s_nop 0
	global_load_lds_dwordx4 v[140:141], off
	s_waitcnt vmcnt(8)
	s_waitcnt lgkmcnt(0)
	s_barrier
	s_setprio 1
	s_waitcnt lgkmcnt(0)
	s_setprio 0
	s_setprio 1
	s_setprio 0
	s_barrier
	s_add_i32 s71, s71, 2
	s_add_u32 s12, s12, 0x100
	s_addc_u32 s13, s13, 0
	s_add_u32 s67, s67, 0x100
	s_addc_u32 s70, s70, 0
	s_cmp_gt_u32 s71, 13
	s_cbranch_scc0 .LBB0_1638
	s_and_b64 vcc, exec, s[18:19]
	s_cbranch_vccz .LBB0_1641
	s_barrier
